# sample pool units: z staging waits vmcnt(32) in the two computing waves (weights waited at the MFMA block)
# baseline (speedup 1.0000x reference)
.LBB0_594:
	s_or_b64 exec, exec, s[48:49]
	s_mov_b32 s37, s73
	s_lshl_b64 s[24:25], s[36:37], 15
	s_add_u32 s24, s51, s24
	v_readlane_b32 s12, v253, 20
	v_bfe_u32 v225, v161, 4, 2
	s_addc_u32 s25, s12, s25
	v_lshlrev_b32_e32 v0, 8, v176
	v_lshl_add_u64 v[2:3], s[24:25], 0, v[0:1]
	v_lshlrev_b32_e32 v0, 4, v225
	v_lshl_add_u64 v[2:3], v[2:3], 0, v[0:1]
	v_lshlrev_b32_e32 v151, 4, v161
	v_and_b32_e32 v151, 0xf0, v151
	v_readfirstlane_b32 s12, v161
	s_cmpk_gt_i32 s12, 0x7f
	s_cbranch_scc1 .Lpw_skip0
	s_movk_i32 s12, 0x1000
	v_add_co_u32_e32 v4, vcc, s12, v2
	s_movk_i32 s12, 0x2000
	s_nop 0
	v_addc_co_u32_e32 v5, vcc, 0, v3, vcc
	v_add_co_u32_e32 v126, vcc, s12, v2
	s_movk_i32 s12, 0x3000
	s_nop 0
	v_addc_co_u32_e32 v127, vcc, 0, v3, vcc
	v_add_co_u32_e32 v6, vcc, s12, v2
	s_movk_i32 s12, 0x4000
	s_nop 0
	v_addc_co_u32_e32 v7, vcc, 0, v3, vcc
	v_add_co_u32_e32 v8, vcc, s12, v2
	s_movk_i32 s12, 0x5000
	s_nop 0
	v_addc_co_u32_e32 v9, vcc, 0, v3, vcc
	global_load_dwordx4 v[98:101], v[2:3], off
	global_load_dwordx4 v[78:81], v[2:3], off offset:64
	global_load_dwordx4 v[66:69], v[2:3], off offset:128
	global_load_dwordx4 v[34:37], v[2:3], off offset:192
	global_load_dwordx4 v[70:73], v[4:5], off offset:64
	global_load_dwordx4 v[74:77], v[4:5], off offset:128
	global_load_dwordx4 v[38:41], v[126:127], off
	global_load_dwordx4 v[42:45], v[126:127], off offset:64
	global_load_dwordx4 v[46:49], v[126:127], off offset:128
	global_load_dwordx4 v[50:53], v[126:127], off offset:192
	global_load_dwordx4 v[122:125], v[4:5], off offset:192
	global_load_dwordx4 v[82:85], v[6:7], off offset:64
	global_load_dwordx4 v[86:89], v[6:7], off offset:128
	global_load_dwordx4 v[90:93], v[6:7], off offset:192
	global_load_dwordx4 v[102:105], v[8:9], off offset:-4096
	global_load_dwordx4 v[54:57], v[8:9], off
	global_load_dwordx4 v[58:61], v[8:9], off offset:64
	global_load_dwordx4 v[62:65], v[8:9], off offset:128
	v_add_co_u32_e32 v4, vcc, s12, v2
	s_movk_i32 s12, 0x6000
	s_nop 0
	v_addc_co_u32_e32 v5, vcc, 0, v3, vcc
	v_add_co_u32_e32 v6, vcc, s12, v2
	s_nop 0
	v_addc_co_u32_e32 v7, vcc, 0, v3, vcc
	global_load_dwordx4 v[118:121], v[8:9], off offset:192
	global_load_dwordx4 v[110:113], v[6:7], off offset:-4096
	global_load_dwordx4 v[106:109], v[4:5], off offset:64
	global_load_dwordx4 v[94:97], v[4:5], off offset:128
	global_load_dwordx4 v[30:33], v[6:7], off
	global_load_dwordx4 v[26:29], v[6:7], off offset:64
	global_load_dwordx4 v[22:25], v[6:7], off offset:128
	global_load_dwordx4 v[18:21], v[6:7], off offset:192
	v_add_co_u32_e32 v2, vcc, 0x7000, v2
	s_nop 0
	v_addc_co_u32_e32 v3, vcc, 0, v3, vcc
	global_load_dwordx4 v[114:117], v[4:5], off offset:192
	global_load_dwordx4 v[14:17], v[2:3], off
	global_load_dwordx4 v[10:13], v[2:3], off offset:64
	global_load_dwordx4 v[6:9], v[2:3], off offset:128
	s_nop 0
	global_load_dwordx4 v[126:129], v[126:127], off offset:-4096
	s_nop 0
	global_load_dwordx4 v[2:5], v[2:3], off offset:192
	s_waitcnt vmcnt(32)
	s_branch .Lpw_skip

.Lpw_skip:
	v_add_u32_e32 v160, 0, v151
	s_and_saveexec_b64 s[48:49], s[0:1]
	s_cbranch_execz .LBB0_613
	s_movk_i32 s0, 0x120
	v_mad_u64_u32 v[150:151], s[0:1], v150, s0, v[160:161]
	s_nop 0
	ds_write_b128 v150, v[134:137]
	s_or_b64 exec, exec, s[48:49]
	s_and_saveexec_b64 s[0:1], s[38:39]
	s_cbranch_execnz .LBB0_614

.LBB0_597:
	s_movk_i32 s12, 0x120
	s_nop 0
	v_mad_u64_u32 v[130:131], s[24:25], v154, s12, v[160:161]
	ds_write_b128 v130, v[142:145]
	s_or_b64 exec, exec, s[0:1]
	s_and_saveexec_b64 s[0:1], s[44:45]
	s_cbranch_execnz .LBB0_616

.LBB0_599:
	s_movk_i32 s12, 0x120
	s_nop 0
	v_mad_u64_u32 v[130:131], s[24:25], v158, s12, v[160:161]
	ds_write_b128 v130, v[146:149]
.LBB0_600:
	s_or_b64 exec, exec, s[0:1]
	v_readfirstlane_b32 s0, v161
	s_ashr_i32 s0, s0, 2
	s_and_b32 s19, s0, -16
	s_cmp_gt_i32 s19, 31
	s_waitcnt lgkmcnt(0)
	s_barrier
	s_cbranch_scc1 .LBB0_622
	s_or_b32 s0, s0, 15
	s_lshl_b32 s23, 2, s36
	v_add_u32_e32 v130, s0, v176
	s_movk_i32 s0, 0x120
	s_cmp_gt_i32 s23, 0
	v_add_u32_e32 v131, 0, v0
	v_mul_lo_u32 v226, v130, s0
	s_cselect_b64 s[38:39], -1, 0
	s_cmp_lt_i32 s23, 1
	v_add_u32_e32 v188, v131, v226
	s_cbranch_scc1 .LBB0_617
	ds_read_b128 v[130:133], v188
	v_readlane_b32 s1, v255, 51
	s_add_i32 s0, s23, -1
	s_waitcnt lgkmcnt(0)
	v_and_b32_e32 v139, 0xffff0000, v130
	v_lshlrev_b32_e32 v138, 16, v130
	v_and_b32_e32 v137, 0xffff0000, v131
	v_lshlrev_b32_e32 v136, 16, v131
	v_and_b32_e32 v135, 0xffff0000, v132
	v_lshlrev_b32_e32 v134, 16, v132
	v_and_b32_e32 v131, 0xffff0000, v133
	v_lshlrev_b32_e32 v130, 16, v133
	v_pk_add_f32 v[132:133], v[130:131], 0 op_sel_hi:[1,0]
	v_pk_add_f32 v[140:141], v[134:135], 0 op_sel_hi:[1,0]
	v_pk_add_f32 v[142:143], v[136:137], 0 op_sel_hi:[1,0]
	v_pk_add_f32 v[144:145], v[138:139], 0 op_sel_hi:[1,0]
	v_add3_u32 v146, v226, v0, s1

.LBB0_614:
	s_movk_i32 s12, 0x120
	s_nop 0
	v_mad_u64_u32 v[134:135], s[24:25], v152, s12, v[160:161]
	ds_write_b128 v134, v[130:133]
	s_or_b64 exec, exec, s[0:1]
	s_and_saveexec_b64 s[0:1], s[42:43]
	s_cbranch_execnz .LBB0_597

.LBB0_616:
	s_movk_i32 s12, 0x120
	s_nop 0
	v_mad_u64_u32 v[130:131], s[24:25], v156, s12, v[160:161]
	ds_write_b128 v130, v[138:141]
	s_or_b64 exec, exec, s[0:1]
	s_and_saveexec_b64 s[0:1], s[46:47]
	s_cbranch_execnz .LBB0_599
	s_branch .LBB0_600

.LBB0_621:
	s_waitcnt vmcnt(0)
	v_cvt_f32_i32_e32 v0, s23
	s_addk_i32 s22, 0x4000
	s_lshl_b32 s72, s72, 1
	v_div_scale_f32 v212, s[0:1], v0, v0, 1.0
	v_rcp_f32_e32 v213, v212
	v_div_scale_f32 v214, vcc, 1.0, v0, 1.0
	v_fma_f32 v215, -v212, v213, 1.0
	v_fmac_f32_e32 v213, v215, v213
	v_mul_f32_e32 v215, v214, v213
	v_fma_f32 v222, -v212, v215, v214
	v_fmac_f32_e32 v215, v222, v213
	v_fma_f32 v212, -v212, v215, v214
	v_div_fmas_f32 v212, v212, v213, v215
	v_div_fixup_f32 v0, v212, v0, 1.0
	v_pk_fma_f32 v[138:139], v[0:1], v[144:145], v[138:139] op_sel_hi:[0,1,1] neg_lo:[0,0,1] neg_hi:[0,0,1]
	v_pk_fma_f32 v[136:137], v[0:1], v[142:143], v[136:137] op_sel_hi:[0,1,1] neg_lo:[0,0,1] neg_hi:[0,0,1]
	v_pk_fma_f32 v[134:135], v[0:1], v[140:141], v[134:135] op_sel_hi:[0,1,1] neg_lo:[0,0,1] neg_hi:[0,0,1]
	v_pk_fma_f32 v[130:131], v[0:1], v[132:133], v[130:131] op_sel_hi:[0,1,1] neg_lo:[0,0,1] neg_hi:[0,0,1]
	v_cvt_pk_bf16_f32 v138, v138, v139
	v_cvt_pk_bf16_f32 v139, v136, v137
	v_cvt_pk_bf16_f32 v140, v134, v135
	v_cvt_pk_bf16_f32 v141, v130, v131
	v_pk_fma_f32 v[154:155], v[0:1], v[160:161], v[154:155] op_sel_hi:[0,1,1] neg_lo:[0,0,1] neg_hi:[0,0,1]
	v_pk_fma_f32 v[152:153], v[0:1], v[158:159], v[152:153] op_sel_hi:[0,1,1] neg_lo:[0,0,1] neg_hi:[0,0,1]
	v_mfma_f32_16x16x32_bf16 v[98:101], v[98:101], v[138:141], 0
	v_fma_f32 v150, v0, v156, -v150
	v_fma_f32 v151, v0, v157, -v151
	v_pk_fma_f32 v[146:147], v[0:1], v[146:147], v[148:149] op_sel_hi:[0,1,1] neg_lo:[0,0,1] neg_hi:[0,0,1]
	v_cvt_pk_bf16_f32 v154, v154, v155
	v_mfma_f32_16x16x32_bf16 v[38:41], v[38:41], v[138:141], 0
	v_cvt_pk_bf16_f32 v155, v152, v153
	v_cvt_pk_bf16_f32 v156, v150, v151
	v_cvt_pk_bf16_f32 v157, v146, v147
	v_pk_fma_f32 v[170:171], v[0:1], v[186:187], v[170:171] op_sel_hi:[0,1,1] neg_lo:[0,0,1] neg_hi:[0,0,1]
	v_pk_fma_f32 v[174:175], v[0:1], v[174:175], v[168:169] op_sel_hi:[0,1,1] neg_lo:[0,0,1] neg_hi:[0,0,1]
	v_mfma_f32_16x16x32_bf16 v[78:81], v[78:81], v[154:157], v[98:101]
	v_fma_f32 v166, v0, v172, -v166
	v_fma_f32 v167, v0, v173, -v167
	v_pk_fma_f32 v[162:163], v[0:1], v[162:163], v[164:165] op_sel_hi:[0,1,1] neg_lo:[0,0,1] neg_hi:[0,0,1]
	v_cvt_pk_bf16_f32 v168, v170, v171
	v_mfma_f32_16x16x32_bf16 v[38:41], v[42:45], v[154:157], v[38:41]
	v_cvt_pk_bf16_f32 v169, v174, v175
	v_cvt_pk_bf16_f32 v170, v166, v167
	v_cvt_pk_bf16_f32 v171, v162, v163
	v_pk_fma_f32 v[130:131], v[0:1], v[202:203], v[188:189] op_sel_hi:[0,1,1] neg_lo:[0,0,1] neg_hi:[0,0,1]
	v_pk_fma_f32 v[98:99], v[0:1], v[200:201], v[192:193] op_sel_hi:[0,1,1] neg_lo:[0,0,1] neg_hi:[0,0,1]
	v_mfma_f32_16x16x32_bf16 v[66:69], v[66:69], v[168:171], v[78:81]
	v_cvt_pk_bf16_f32 v130, v130, v131
	v_cvt_pk_bf16_f32 v131, v98, v99
	v_pk_fma_f32 v[98:99], v[0:1], v[198:199], v[194:195] op_sel_hi:[0,1,1] neg_lo:[0,0,1] neg_hi:[0,0,1]
	v_mfma_f32_16x16x32_bf16 v[38:41], v[46:49], v[168:171], v[38:41]
	v_fma_f32 v78, v0, v190, -v196
	v_fma_f32 v79, v0, v191, -v197
	v_cvt_pk_bf16_f32 v132, v98, v99
	v_cvt_pk_bf16_f32 v133, v78, v79
	v_mfma_f32_16x16x32_bf16 v[42:45], v[102:105], v[138:141], 0
	v_or_b32_e32 v0, s22, v176
	v_mfma_f32_16x16x32_bf16 v[34:37], v[34:37], v[130:133], v[66:69]
	v_mfma_f32_16x16x32_bf16 v[66:69], v[126:129], v[138:141], 0
	v_mfma_f32_16x16x32_bf16 v[38:41], v[50:53], v[130:133], v[38:41]
	s_nop 5
	v_cvt_pk_bf16_f32 v34, v34, v35
	v_cvt_pk_bf16_f32 v35, v36, v37
	v_mfma_f32_16x16x32_bf16 v[46:49], v[54:57], v[138:141], 0
	v_add_u32_e32 v54, s19, v0
	v_ashrrev_i32_e32 v55, 31, v54
	v_lshlrev_b64 v[54:55], 11, v[54:55]
	v_mfma_f32_16x16x32_bf16 v[50:53], v[110:113], v[138:141], 0
	v_lshl_add_u64 v[54:55], s[76:77], 0, v[54:55]
	v_lshl_add_u64 v[54:55], v[54:55], 0, s[72:73]
	v_lshlrev_b32_e32 v0, 3, v225
	v_mfma_f32_16x16x32_bf16 v[30:33], v[30:33], v[138:141], 0
	v_lshl_add_u64 v[54:55], v[54:55], 0, v[0:1]
	global_store_dwordx2 v[54:55], v[34:35], off
	v_mfma_f32_16x16x32_bf16 v[14:17], v[14:17], v[138:141], 0
	v_mfma_f32_16x16x32_bf16 v[42:45], v[82:85], v[154:157], v[42:45]
	v_mfma_f32_16x16x32_bf16 v[66:69], v[70:73], v[154:157], v[66:69]
	v_mfma_f32_16x16x32_bf16 v[46:49], v[58:61], v[154:157], v[46:49]
	v_mfma_f32_16x16x32_bf16 v[50:53], v[106:109], v[154:157], v[50:53]
	v_mfma_f32_16x16x32_bf16 v[26:29], v[26:29], v[154:157], v[30:33]
	v_mfma_f32_16x16x32_bf16 v[10:13], v[10:13], v[154:157], v[14:17]
	v_mfma_f32_16x16x32_bf16 v[42:45], v[86:89], v[168:171], v[42:45]
	v_mfma_f32_16x16x32_bf16 v[66:69], v[74:77], v[168:171], v[66:69]
	v_mfma_f32_16x16x32_bf16 v[46:49], v[62:65], v[168:171], v[46:49]
	v_mfma_f32_16x16x32_bf16 v[50:53], v[94:97], v[168:171], v[50:53]
	v_mfma_f32_16x16x32_bf16 v[22:25], v[22:25], v[168:171], v[26:29]
	v_mfma_f32_16x16x32_bf16 v[6:9], v[6:9], v[168:171], v[10:13]
	s_nop 1
	v_cvt_pk_bf16_f32 v26, v38, v39
	v_cvt_pk_bf16_f32 v27, v40, v41
	global_store_dwordx2 v[54:55], v[26:27], off offset:64
	v_mfma_f32_16x16x32_bf16 v[42:45], v[90:93], v[130:133], v[42:45]
	v_mfma_f32_16x16x32_bf16 v[66:69], v[122:125], v[130:133], v[66:69]
	v_mfma_f32_16x16x32_bf16 v[46:49], v[118:121], v[130:133], v[46:49]
	v_mfma_f32_16x16x32_bf16 v[50:53], v[114:117], v[130:133], v[50:53]
	s_nop 5
	v_cvt_pk_bf16_f32 v30, v66, v67
	v_cvt_pk_bf16_f32 v31, v68, v69
	global_store_dwordx2 v[54:55], v[30:31], off offset:32
	v_mfma_f32_16x16x32_bf16 v[18:21], v[18:21], v[130:133], v[22:25]
	v_mfma_f32_16x16x32_bf16 v[2:5], v[2:5], v[130:133], v[6:9]
	s_nop 1
	v_cvt_pk_bf16_f32 v22, v42, v43
	v_cvt_pk_bf16_f32 v23, v44, v45
	global_store_dwordx2 v[54:55], v[22:23], off offset:96
	v_cvt_pk_bf16_f32 v22, v46, v47
	v_cvt_pk_bf16_f32 v23, v48, v49
	v_cvt_pk_bf16_f32 v14, v50, v51
	v_cvt_pk_bf16_f32 v15, v52, v53
	v_cvt_pk_bf16_f32 v10, v18, v19
	v_cvt_pk_bf16_f32 v11, v20, v21
	v_cvt_pk_bf16_f32 v2, v2, v3
	v_cvt_pk_bf16_f32 v3, v4, v5
	global_store_dwordx2 v[54:55], v[22:23], off offset:128
	global_store_dwordx2 v[54:55], v[14:15], off offset:160
	global_store_dwordx2 v[54:55], v[10:11], off offset:192
	global_store_dwordx2 v[54:55], v[2:3], off offset:224
